# previous + nt hint on the once-read adaLN weight loads in phase 0
# speedup vs baseline: 1.0248x; 1.0026x over previous
; DI float siluf(float v) { return v * __builtin_amdgcn_rcpf(1.f + __expf(-v)); }
; DI void phase0(const Prm& p, bf16_t* smraw) {
;     ...
;   for (int u = b; u < 384; u += G) {
;     const int l = u / 96, cg0 = (u % 96) * 64, kq = tid >> 4, cq = tid & 15;
;     const float* w = p.ada_w + ((size_t)l * 1024 + kq * 32) * 6144 + cg0 + cq * 4;
;     float4 a0 = make_float4(0, 0, 0, 0), a1 = a0;
; #pragma unroll 8
;     for (int k = 0; k < 32; ++k) {
;       const float4 wv = *(const float4*)(w + (size_t)k * 6144);
;       const float s0 = siluf(p.c[kq * 32 + k]), s1 = siluf(p.cctx[kq * 32 + k]);
;       a0.x += s0 * wv.x; a0.y += s0 * wv.y; a0.z += s0 * wv.z; a0.w += s0 * wv.w;
;       a1.x += s1 * wv.x; a1.y += s1 * wv.y; a1.z += s1 * wv.z; a1.w += s1 * wv.w;
;     }
.LBB0_21:
	v_lshl_add_u64 v[42:43], s[18:19], 0, v[12:13]
	v_lshl_add_u64 v[40:41], v[16:17], 0, s[16:17]
	v_lshl_add_u64 v[44:45], s[20:21], 0, v[12:13]
	global_load_dwordx4 v[20:23], v[42:43], off
	global_load_dwordx4 v[24:27], v[44:45], off
	global_load_dwordx4 v[28:31], v[42:43], off offset:16
	global_load_dwordx4 v[32:35], v[44:45], off offset:16
	global_load_dwordx4 v[36:39], v[40:41], off nt
	v_add_co_u32_e64 v68, s[4:5], s25, v40
	s_add_u32 s20, s20, 32
	s_nop 0
	v_addc_co_u32_e64 v69, s[4:5], 0, v41, s[4:5]
	v_add_co_u32_e64 v70, s[4:5], s26, v40
	s_addc_u32 s21, s21, 0
	s_nop 0
	v_addc_co_u32_e64 v71, s[4:5], 0, v41, s[4:5]
	v_add_co_u32_e64 v72, s[4:5], s27, v40
	s_add_u32 s18, s18, 32
	s_nop 0
	v_addc_co_u32_e64 v73, s[4:5], 0, v41, s[4:5]
	v_add_co_u32_e64 v74, s[4:5], s28, v40
	s_addc_u32 s19, s19, 0
	s_nop 0
	v_addc_co_u32_e64 v75, s[4:5], 0, v41, s[4:5]
	v_add_co_u32_e64 v76, s[4:5], s29, v40
	s_add_u32 s16, s16, 0x30000
	s_nop 0
	v_addc_co_u32_e64 v77, s[4:5], 0, v41, s[4:5]
	v_add_co_u32_e64 v78, s[4:5], s30, v40
	s_addc_u32 s17, s17, 0
	s_nop 0
	v_addc_co_u32_e64 v79, s[4:5], 0, v41, s[4:5]
	v_add_co_u32_e64 v80, s[4:5], s31, v40
	s_cmp_eq_u32 s16, 0xc0000
	s_nop 0
	v_addc_co_u32_e64 v81, s[4:5], 0, v41, s[4:5]
	global_load_dwordx4 v[40:43], v[68:69], off nt
	global_load_dwordx4 v[44:47], v[70:71], off nt
	global_load_dwordx4 v[48:51], v[72:73], off nt
	global_load_dwordx4 v[52:55], v[74:75], off nt
	global_load_dwordx4 v[56:59], v[76:77], off nt
	global_load_dwordx4 v[60:63], v[78:79], off nt
	global_load_dwordx4 v[64:67], v[80:81], off nt
	s_waitcnt vmcnt(11)
	v_mul_f32_e32 v68, 0xbfb8aa3b, v20
	s_waitcnt vmcnt(10)
	v_mul_f32_e32 v69, 0xbfb8aa3b, v24
	v_mul_f32_e32 v70, 0xbfb8aa3b, v21
	v_mul_f32_e32 v71, 0xbfb8aa3b, v25
	v_exp_f32_e32 v68, v68
	v_exp_f32_e32 v69, v69
	v_mul_f32_e32 v72, 0xbfb8aa3b, v22
	v_mul_f32_e32 v73, 0xbfb8aa3b, v26
	v_exp_f32_e32 v70, v70
	v_exp_f32_e32 v71, v71
	v_mul_f32_e32 v74, 0xbfb8aa3b, v23
	v_mul_f32_e32 v75, 0xbfb8aa3b, v27
	v_exp_f32_e32 v72, v72
	v_exp_f32_e32 v73, v73
	s_waitcnt vmcnt(9)
	v_mul_f32_e32 v76, 0xbfb8aa3b, v28
	s_waitcnt vmcnt(8)
	v_mul_f32_e32 v77, 0xbfb8aa3b, v32
	v_exp_f32_e32 v74, v74
	v_exp_f32_e32 v75, v75
	v_mul_f32_e32 v78, 0xbfb8aa3b, v29
	v_mul_f32_e32 v79, 0xbfb8aa3b, v33
	v_exp_f32_e32 v76, v76
	v_exp_f32_e32 v77, v77
	v_add_f32_e32 v68, 1.0, v68
	v_add_f32_e32 v69, 1.0, v69
	v_mul_f32_e32 v80, 0xbfb8aa3b, v30
	v_mul_f32_e32 v81, 0xbfb8aa3b, v34
	v_exp_f32_e32 v78, v78
	v_exp_f32_e32 v79, v79
	v_add_f32_e32 v70, 1.0, v70
	v_add_f32_e32 v71, 1.0, v71
	v_rcp_f32_e32 v68, v68
	v_rcp_f32_e32 v69, v69
	v_mul_f32_e32 v82, 0xbfb8aa3b, v31
	v_mul_f32_e32 v83, 0xbfb8aa3b, v35
	v_exp_f32_e32 v80, v80
	v_exp_f32_e32 v81, v81
	v_add_f32_e32 v72, 1.0, v72
	v_add_f32_e32 v73, 1.0, v73
	v_rcp_f32_e32 v70, v70
	v_rcp_f32_e32 v71, v71
	v_exp_f32_e32 v82, v82
	v_exp_f32_e32 v83, v83
	v_add_f32_e32 v74, 1.0, v74
	v_add_f32_e32 v75, 1.0, v75
	v_rcp_f32_e32 v72, v72
	v_rcp_f32_e32 v73, v73
	v_add_f32_e32 v76, 1.0, v76
	v_add_f32_e32 v77, 1.0, v77
	v_rcp_f32_e32 v74, v74
	v_rcp_f32_e32 v75, v75
	v_add_f32_e32 v78, 1.0, v78
	v_add_f32_e32 v79, 1.0, v79
	v_rcp_f32_e32 v76, v76
	v_rcp_f32_e32 v77, v77
	v_mul_f32_e32 v20, v20, v68
	v_mul_f32_e32 v24, v24, v69
	v_add_f32_e32 v80, 1.0, v80
	v_add_f32_e32 v81, 1.0, v81
	v_rcp_f32_e32 v78, v78
	v_rcp_f32_e32 v79, v79
	v_mul_f32_e32 v68, v21, v70
	v_mul_f32_e32 v70, v25, v71
	s_waitcnt vmcnt(7)
	v_pk_fma_f32 v[4:5], v[36:37], v[20:21], v[4:5] op_sel_hi:[1,0,1]
	v_pk_fma_f32 v[6:7], v[38:39], v[20:21], v[6:7] op_sel_hi:[1,0,1]
	v_pk_fma_f32 v[0:1], v[36:37], v[24:25], v[0:1] op_sel_hi:[1,0,1]
	v_pk_fma_f32 v[2:3], v[38:39], v[24:25], v[2:3] op_sel_hi:[1,0,1]
	v_add_f32_e32 v82, 1.0, v82
	v_add_f32_e32 v83, 1.0, v83
	v_rcp_f32_e32 v80, v80
	v_rcp_f32_e32 v81, v81
	v_mul_f32_e32 v22, v22, v72
	v_mul_f32_e32 v26, v26, v73
	s_waitcnt vmcnt(6)
	v_pk_fma_f32 v[4:5], v[40:41], v[68:69], v[4:5] op_sel_hi:[1,0,1]
	v_pk_fma_f32 v[6:7], v[42:43], v[68:69], v[6:7] op_sel_hi:[1,0,1]
	v_pk_fma_f32 v[0:1], v[40:41], v[70:71], v[0:1] op_sel_hi:[1,0,1]
	v_pk_fma_f32 v[2:3], v[42:43], v[70:71], v[2:3] op_sel_hi:[1,0,1]
	v_rcp_f32_e32 v82, v82
	v_rcp_f32_e32 v83, v83
	v_mul_f32_e32 v72, v23, v74
	v_mul_f32_e32 v74, v27, v75
	s_waitcnt vmcnt(5)
	v_pk_fma_f32 v[4:5], v[44:45], v[22:23], v[4:5] op_sel_hi:[1,0,1]
	v_pk_fma_f32 v[6:7], v[46:47], v[22:23], v[6:7] op_sel_hi:[1,0,1]
	v_pk_fma_f32 v[0:1], v[44:45], v[26:27], v[0:1] op_sel_hi:[1,0,1]
	v_pk_fma_f32 v[2:3], v[46:47], v[26:27], v[2:3] op_sel_hi:[1,0,1]
	v_mul_f32_e32 v28, v28, v76
	v_mul_f32_e32 v32, v32, v77
	s_waitcnt vmcnt(4)
	v_pk_fma_f32 v[4:5], v[48:49], v[72:73], v[4:5] op_sel_hi:[1,0,1]
	v_pk_fma_f32 v[6:7], v[50:51], v[72:73], v[6:7] op_sel_hi:[1,0,1]
	v_pk_fma_f32 v[0:1], v[48:49], v[74:75], v[0:1] op_sel_hi:[1,0,1]
	v_pk_fma_f32 v[2:3], v[50:51], v[74:75], v[2:3] op_sel_hi:[1,0,1]
	v_mul_f32_e32 v76, v29, v78
	v_mul_f32_e32 v78, v33, v79
	s_waitcnt vmcnt(3)
	v_pk_fma_f32 v[4:5], v[52:53], v[28:29], v[4:5] op_sel_hi:[1,0,1]
	v_pk_fma_f32 v[6:7], v[54:55], v[28:29], v[6:7] op_sel_hi:[1,0,1]
	v_pk_fma_f32 v[0:1], v[52:53], v[32:33], v[0:1] op_sel_hi:[1,0,1]
	v_pk_fma_f32 v[2:3], v[54:55], v[32:33], v[2:3] op_sel_hi:[1,0,1]
	v_mul_f32_e32 v30, v30, v80
	v_mul_f32_e32 v34, v34, v81
	s_waitcnt vmcnt(2)
	v_pk_fma_f32 v[4:5], v[56:57], v[76:77], v[4:5] op_sel_hi:[1,0,1]
	v_pk_fma_f32 v[6:7], v[58:59], v[76:77], v[6:7] op_sel_hi:[1,0,1]
	v_pk_fma_f32 v[0:1], v[56:57], v[78:79], v[0:1] op_sel_hi:[1,0,1]
	v_pk_fma_f32 v[2:3], v[58:59], v[78:79], v[2:3] op_sel_hi:[1,0,1]
	v_mul_f32_e32 v80, v31, v82
	v_mul_f32_e32 v82, v35, v83
	s_waitcnt vmcnt(1)
	v_pk_fma_f32 v[4:5], v[60:61], v[30:31], v[4:5] op_sel_hi:[1,0,1]
	v_pk_fma_f32 v[6:7], v[62:63], v[30:31], v[6:7] op_sel_hi:[1,0,1]
	v_pk_fma_f32 v[0:1], v[60:61], v[34:35], v[0:1] op_sel_hi:[1,0,1]
	v_pk_fma_f32 v[2:3], v[62:63], v[34:35], v[2:3] op_sel_hi:[1,0,1]
	s_waitcnt vmcnt(0)
	v_pk_fma_f32 v[4:5], v[64:65], v[80:81], v[4:5] op_sel_hi:[1,0,1]
	v_pk_fma_f32 v[6:7], v[66:67], v[80:81], v[6:7] op_sel_hi:[1,0,1]
	v_pk_fma_f32 v[0:1], v[64:65], v[82:83], v[0:1] op_sel_hi:[1,0,1]
	v_pk_fma_f32 v[2:3], v[66:67], v[82:83], v[2:3] op_sel_hi:[1,0,1]
	s_cbranch_scc0 .LBB0_21
; DI void phase0(const Prm& p, bf16_t* smraw) {
;     ...
;     __syncthreads();
;     *(float4*)(smf + (kq * 16 + cq) * 8) = a0; *(float4*)(smf + (kq * 16 + cq) * 8 + 4) = a1;
;     __syncthreads();
;     if (tid < 128) {
;       const int wsel = tid >> 6, col = tid & 63; float s = 0.f;
;       for (int q = 0; q < 32; ++q) s += smf[(q * 16 + (col >> 2)) * 8 + wsel * 4 + (col & 3)];
;       float* mod = (float*)(p.ws + O_MOD);
;       mod[(size_t)(l * 2 + wsel) * 6144 + cg0 + col] = s + p.ada_b[(size_t)l * 6144 + cg0 + col];
;     }
;     __syncthreads();
	s_barrier
	ds_write_b128 v9, v[4:7]
	ds_write_b128 v9, v[0:3] offset:16
	s_waitcnt lgkmcnt(0)
	s_barrier
	s_and_saveexec_b64 s[4:5], vcc
	s_cbranch_execz .LBB0_19
	s_mul_i32 s17, s34, 0x6000
	s_mul_hi_i32 s16, s34, 0x6000
	s_add_u32 s17, s12, s17
	s_addc_u32 s18, s13, s16
	s_add_u32 s16, s17, s10
	s_addc_u32 s17, s18, s11
	global_load_dword v44, v10, s[16:17]
	ds_read2st64_b32 v[0:1], v19 offset1:2
	ds_read2st64_b32 v[2:3], v19 offset0:4 offset1:6
	ds_read2st64_b32 v[4:5], v19 offset0:8 offset1:10
	ds_read2st64_b32 v[6:7], v19 offset0:12 offset1:14
	ds_read2st64_b32 v[16:17], v19 offset0:16 offset1:18
	ds_read2st64_b32 v[20:21], v19 offset0:20 offset1:22
	ds_read2st64_b32 v[22:23], v19 offset0:24 offset1:26
	ds_read2st64_b32 v[24:25], v19 offset0:28 offset1:30
	ds_read2st64_b32 v[26:27], v19 offset0:32 offset1:34
	ds_read2st64_b32 v[28:29], v19 offset0:36 offset1:38
	ds_read2st64_b32 v[30:31], v19 offset0:40 offset1:42
	ds_read2st64_b32 v[32:33], v19 offset0:44 offset1:46
	ds_read2st64_b32 v[34:35], v19 offset0:48 offset1:50
	ds_read2st64_b32 v[36:37], v19 offset0:52 offset1:54
	ds_read2st64_b32 v[38:39], v19 offset0:56 offset1:58
	ds_read2st64_b32 v[40:41], v19 offset0:60 offset1:62
	s_waitcnt lgkmcnt(14)
	v_add_f32_e32 v0, 0, v0
	v_add_f32_e32 v0, v0, v1
	v_add_f32_e32 v0, v0, v2
	v_add_f32_e32 v0, v0, v3
	s_waitcnt lgkmcnt(13)
	v_add_f32_e32 v0, v0, v4
	v_add_f32_e32 v0, v0, v5
	s_waitcnt lgkmcnt(12)
	v_add_f32_e32 v0, v0, v6
	v_add_f32_e32 v0, v0, v7
	s_waitcnt lgkmcnt(11)
	v_add_f32_e32 v0, v0, v16
	v_add_f32_e32 v0, v0, v17
	s_waitcnt lgkmcnt(10)
	v_add_f32_e32 v0, v0, v20
	v_add_f32_e32 v0, v0, v21
	s_waitcnt lgkmcnt(9)
	v_add_f32_e32 v0, v0, v22
	v_add_f32_e32 v0, v0, v23
	s_waitcnt lgkmcnt(8)
	v_add_f32_e32 v0, v0, v24
	v_add_f32_e32 v0, v0, v25
	s_waitcnt lgkmcnt(7)
	v_add_f32_e32 v0, v0, v26
	v_add_f32_e32 v0, v0, v27
	s_waitcnt lgkmcnt(6)
	v_add_f32_e32 v0, v0, v28
	v_add_f32_e32 v0, v0, v29
	s_waitcnt lgkmcnt(5)
	v_add_f32_e32 v0, v0, v30
	v_add_f32_e32 v0, v0, v31
	s_waitcnt lgkmcnt(4)
	v_add_f32_e32 v0, v0, v32
	v_add_f32_e32 v0, v0, v33
	s_waitcnt lgkmcnt(3)
	v_add_f32_e32 v0, v0, v34
	v_add_f32_e32 v0, v0, v35
	s_waitcnt lgkmcnt(2)
	v_add_f32_e32 v0, v0, v36
	v_add_f32_e32 v0, v0, v37
	s_waitcnt lgkmcnt(1)
	v_add_f32_e32 v0, v0, v38
	v_lshl_add_u32 v45, s34, 1, v18
	v_mov_b64_e32 v[42:43], s[14:15]
	v_add_f32_e32 v0, v0, v39
	v_mad_i64_i32 v[42:43], s[16:17], v45, s25, v[42:43]
	s_waitcnt lgkmcnt(0)
	v_add_f32_e32 v0, v0, v40
	v_lshl_add_u64 v[42:43], v[42:43], 0, s[10:11]
	v_add_f32_e32 v0, v0, v41
	s_waitcnt vmcnt(0)
	v_add_f32_e32 v2, v0, v44
	v_lshl_add_u64 v[0:1], v[42:43], 0, v[10:11]
	global_store_dword v[0:1], v2, off
	s_branch .LBB0_19
